# p2_pre (weight transposes + p->bf16) runs in waves 1-7 while wave 0 waits in the post-P1 grid barrier; its trailing barrier closes the grid barrier
# speedup vs baseline: 1.0124x; 1.0001x over previous
.LBB0_332:
	s_or_b64 exec, exec, s[4:5]
	s_mov_b32 s16, s33
	s_mov_b32 s4, -1
	s_waitcnt lgkmcnt(0)
	s_mov_b32 s19, s2
	v_mbcnt_lo_u32_b32 v0, s4, 0
	v_mbcnt_hi_u32_b32 v0, s4, v0
	v_lshl_add_u32 v2, s16, 6, v0
	s_mov_b32 s18, s3
	s_and_b32 s4, s18, 7
	s_cmp_lg_u32 s4, 0
	s_cbranch_scc1 .LBB0_334
	s_ashr_i32 s5, s19, 31
	s_lshr_b32 s5, s5, 29
	s_add_i32 s5, s19, s5
	s_ashr_i32 s6, s5, 3
	s_and_b32 s5, s5, -8
	s_ashr_i32 s4, s18, 3
	s_sub_i32 s5, s19, s5
	s_mul_i32 s4, s5, s4
	s_add_i32 s19, s4, s6
